# GLA prep phase: prefetched k/q taken over after the token loop; the loop-back wait covers the gate vectors only
# baseline (speedup 1.0000x reference)
.Lp7_item:
	ds_write_b128 v9, v[4:7]
	ds_read_b128 v[216:219], v78 offset:0
	ds_read_b128 v[220:223], v78 offset:16
	ds_read_b128 v[224:227], v78 offset:32
	ds_read_b128 v[228:231], v78 offset:48
	ds_read_b128 v[232:235], v78 offset:64
	ds_read_b128 v[236:239], v78 offset:80
	ds_read_b128 v[240:243], v78 offset:96
	ds_read_b128 v[244:247], v78 offset:112
	s_waitcnt lgkmcnt(0)
	v_pk_fma_f32 v[128:129], v[10:11], v[216:217], v[74:75] op_sel_hi:[1,0,1]
	v_pk_fma_f32 v[128:129], v[12:13], v[216:217], v[128:129] op_sel:[0,1,0] op_sel_hi:[1,1,1]
	v_pk_fma_f32 v[128:129], v[14:15], v[218:219], v[128:129] op_sel_hi:[1,0,1]
	v_pk_fma_f32 v[128:129], v[16:17], v[218:219], v[128:129] op_sel:[0,1,0] op_sel_hi:[1,1,1]
	v_pk_fma_f32 v[128:129], v[18:19], v[220:221], v[128:129] op_sel_hi:[1,0,1]
	v_pk_fma_f32 v[128:129], v[20:21], v[220:221], v[128:129] op_sel:[0,1,0] op_sel_hi:[1,1,1]
	v_pk_fma_f32 v[128:129], v[22:23], v[222:223], v[128:129] op_sel_hi:[1,0,1]
	v_pk_fma_f32 v[128:129], v[24:25], v[222:223], v[128:129] op_sel:[0,1,0] op_sel_hi:[1,1,1]
	v_pk_fma_f32 v[128:129], v[26:27], v[224:225], v[128:129] op_sel_hi:[1,0,1]
	v_pk_fma_f32 v[128:129], v[28:29], v[224:225], v[128:129] op_sel:[0,1,0] op_sel_hi:[1,1,1]
	v_pk_fma_f32 v[128:129], v[30:31], v[226:227], v[128:129] op_sel_hi:[1,0,1]
	v_pk_fma_f32 v[128:129], v[32:33], v[226:227], v[128:129] op_sel:[0,1,0] op_sel_hi:[1,1,1]
	v_pk_fma_f32 v[128:129], v[34:35], v[228:229], v[128:129] op_sel_hi:[1,0,1]
	v_pk_fma_f32 v[128:129], v[36:37], v[228:229], v[128:129] op_sel:[0,1,0] op_sel_hi:[1,1,1]
	v_pk_fma_f32 v[128:129], v[38:39], v[230:231], v[128:129] op_sel_hi:[1,0,1]
	v_pk_fma_f32 v[128:129], v[40:41], v[230:231], v[128:129] op_sel:[0,1,0] op_sel_hi:[1,1,1]
	ds_read_b128 v[216:219], v78 offset:128
	ds_read_b128 v[220:223], v78 offset:144
	ds_read_b128 v[224:227], v78 offset:160
	ds_read_b128 v[228:231], v78 offset:176
	v_pk_fma_f32 v[130:131], v[42:43], v[232:233], v[76:77] op_sel_hi:[1,0,1]
	v_pk_fma_f32 v[130:131], v[44:45], v[232:233], v[130:131] op_sel:[0,1,0] op_sel_hi:[1,1,1]
	v_pk_fma_f32 v[130:131], v[46:47], v[234:235], v[130:131] op_sel_hi:[1,0,1]
	v_pk_fma_f32 v[130:131], v[48:49], v[234:235], v[130:131] op_sel:[0,1,0] op_sel_hi:[1,1,1]
	v_pk_fma_f32 v[130:131], v[50:51], v[236:237], v[130:131] op_sel_hi:[1,0,1]
	v_pk_fma_f32 v[130:131], v[52:53], v[236:237], v[130:131] op_sel:[0,1,0] op_sel_hi:[1,1,1]
	v_pk_fma_f32 v[130:131], v[54:55], v[238:239], v[130:131] op_sel_hi:[1,0,1]
	v_pk_fma_f32 v[130:131], v[56:57], v[238:239], v[130:131] op_sel:[0,1,0] op_sel_hi:[1,1,1]
	v_pk_fma_f32 v[130:131], v[58:59], v[240:241], v[130:131] op_sel_hi:[1,0,1]
	v_pk_fma_f32 v[130:131], v[60:61], v[240:241], v[130:131] op_sel:[0,1,0] op_sel_hi:[1,1,1]
	v_pk_fma_f32 v[130:131], v[62:63], v[242:243], v[130:131] op_sel_hi:[1,0,1]
	v_pk_fma_f32 v[130:131], v[64:65], v[242:243], v[130:131] op_sel:[0,1,0] op_sel_hi:[1,1,1]
	v_pk_fma_f32 v[130:131], v[66:67], v[244:245], v[130:131] op_sel_hi:[1,0,1]
	v_pk_fma_f32 v[130:131], v[68:69], v[244:245], v[130:131] op_sel:[0,1,0] op_sel_hi:[1,1,1]
	v_pk_fma_f32 v[130:131], v[70:71], v[246:247], v[130:131] op_sel_hi:[1,0,1]
	v_pk_fma_f32 v[130:131], v[72:73], v[246:247], v[130:131] op_sel:[0,1,0] op_sel_hi:[1,1,1]
	ds_read_b128 v[232:235], v78 offset:192
	ds_read_b128 v[236:239], v78 offset:208
	ds_read_b128 v[240:243], v78 offset:224
	ds_read_b128 v[244:247], v78 offset:240
	v_pk_mul_f32 v[132:133], v[128:129], s[36:37] op_sel_hi:[1,0]
	v_pk_mul_f32 v[134:135], v[130:131], s[36:37] op_sel_hi:[1,0]
	v_exp_f32_e64 v132, -|v132|
	v_exp_f32_e64 v133, -|v133|
	v_exp_f32_e64 v134, -|v134|
	v_exp_f32_e64 v135, -|v135|
	v_pk_add_f32 v[132:133], v[132:133], 1.0 op_sel_hi:[1,0]
	v_pk_add_f32 v[134:135], v[134:135], 1.0 op_sel_hi:[1,0]
	v_log_f32_e32 v136, v132
	v_log_f32_e32 v137, v133
	v_log_f32_e32 v138, v134
	v_log_f32_e32 v139, v135
	v_min_f32_e32 v128, 0, v128
	v_min_f32_e32 v129, 0, v129
	v_min_f32_e32 v130, 0, v130
	v_min_f32_e32 v131, 0, v131
	v_pk_fma_f32 v[96:97], v[136:137], s[36:37], v[128:129] op_sel:[0,1,0] op_sel_hi:[1,1,1]
	v_pk_fma_f32 v[112:113], v[138:139], s[36:37], v[130:131] op_sel:[0,1,0] op_sel_hi:[1,1,1]
	s_waitcnt lgkmcnt(0)
	v_pk_fma_f32 v[128:129], v[10:11], v[216:217], v[74:75] op_sel_hi:[1,0,1]
	v_pk_fma_f32 v[128:129], v[12:13], v[216:217], v[128:129] op_sel:[0,1,0] op_sel_hi:[1,1,1]
	v_pk_fma_f32 v[128:129], v[14:15], v[218:219], v[128:129] op_sel_hi:[1,0,1]
	v_pk_fma_f32 v[128:129], v[16:17], v[218:219], v[128:129] op_sel:[0,1,0] op_sel_hi:[1,1,1]
	v_pk_fma_f32 v[128:129], v[18:19], v[220:221], v[128:129] op_sel_hi:[1,0,1]
	v_pk_fma_f32 v[128:129], v[20:21], v[220:221], v[128:129] op_sel:[0,1,0] op_sel_hi:[1,1,1]
	v_pk_fma_f32 v[128:129], v[22:23], v[222:223], v[128:129] op_sel_hi:[1,0,1]
	v_pk_fma_f32 v[128:129], v[24:25], v[222:223], v[128:129] op_sel:[0,1,0] op_sel_hi:[1,1,1]
	v_pk_fma_f32 v[128:129], v[26:27], v[224:225], v[128:129] op_sel_hi:[1,0,1]
	v_pk_fma_f32 v[128:129], v[28:29], v[224:225], v[128:129] op_sel:[0,1,0] op_sel_hi:[1,1,1]
	v_pk_fma_f32 v[128:129], v[30:31], v[226:227], v[128:129] op_sel_hi:[1,0,1]
	v_pk_fma_f32 v[128:129], v[32:33], v[226:227], v[128:129] op_sel:[0,1,0] op_sel_hi:[1,1,1]
	v_pk_fma_f32 v[128:129], v[34:35], v[228:229], v[128:129] op_sel_hi:[1,0,1]
	v_pk_fma_f32 v[128:129], v[36:37], v[228:229], v[128:129] op_sel:[0,1,0] op_sel_hi:[1,1,1]
	v_pk_fma_f32 v[128:129], v[38:39], v[230:231], v[128:129] op_sel_hi:[1,0,1]
	v_pk_fma_f32 v[128:129], v[40:41], v[230:231], v[128:129] op_sel:[0,1,0] op_sel_hi:[1,1,1]
	ds_read_b128 v[216:219], v78 offset:256
	ds_read_b128 v[220:223], v78 offset:272
	ds_read_b128 v[224:227], v78 offset:288
	ds_read_b128 v[228:231], v78 offset:304
	v_pk_fma_f32 v[130:131], v[42:43], v[232:233], v[76:77] op_sel_hi:[1,0,1]
	v_pk_fma_f32 v[130:131], v[44:45], v[232:233], v[130:131] op_sel:[0,1,0] op_sel_hi:[1,1,1]
	v_pk_fma_f32 v[130:131], v[46:47], v[234:235], v[130:131] op_sel_hi:[1,0,1]
	v_pk_fma_f32 v[130:131], v[48:49], v[234:235], v[130:131] op_sel:[0,1,0] op_sel_hi:[1,1,1]
	v_pk_fma_f32 v[130:131], v[50:51], v[236:237], v[130:131] op_sel_hi:[1,0,1]
	v_pk_fma_f32 v[130:131], v[52:53], v[236:237], v[130:131] op_sel:[0,1,0] op_sel_hi:[1,1,1]
	v_pk_fma_f32 v[130:131], v[54:55], v[238:239], v[130:131] op_sel_hi:[1,0,1]
	v_pk_fma_f32 v[130:131], v[56:57], v[238:239], v[130:131] op_sel:[0,1,0] op_sel_hi:[1,1,1]
	v_pk_fma_f32 v[130:131], v[58:59], v[240:241], v[130:131] op_sel_hi:[1,0,1]
	v_pk_fma_f32 v[130:131], v[60:61], v[240:241], v[130:131] op_sel:[0,1,0] op_sel_hi:[1,1,1]
	v_pk_fma_f32 v[130:131], v[62:63], v[242:243], v[130:131] op_sel_hi:[1,0,1]
	v_pk_fma_f32 v[130:131], v[64:65], v[242:243], v[130:131] op_sel:[0,1,0] op_sel_hi:[1,1,1]
	v_pk_fma_f32 v[130:131], v[66:67], v[244:245], v[130:131] op_sel_hi:[1,0,1]
	v_pk_fma_f32 v[130:131], v[68:69], v[244:245], v[130:131] op_sel:[0,1,0] op_sel_hi:[1,1,1]
	v_pk_fma_f32 v[130:131], v[70:71], v[246:247], v[130:131] op_sel_hi:[1,0,1]
	v_pk_fma_f32 v[130:131], v[72:73], v[246:247], v[130:131] op_sel:[0,1,0] op_sel_hi:[1,1,1]
	ds_read_b128 v[232:235], v78 offset:320
	ds_read_b128 v[236:239], v78 offset:336
	ds_read_b128 v[240:243], v78 offset:352
	ds_read_b128 v[244:247], v78 offset:368
	v_pk_mul_f32 v[132:133], v[128:129], s[36:37] op_sel_hi:[1,0]
	v_pk_mul_f32 v[134:135], v[130:131], s[36:37] op_sel_hi:[1,0]
	v_exp_f32_e64 v132, -|v132|
	v_exp_f32_e64 v133, -|v133|
	v_exp_f32_e64 v134, -|v134|
	v_exp_f32_e64 v135, -|v135|
	v_pk_add_f32 v[132:133], v[132:133], 1.0 op_sel_hi:[1,0]
	v_pk_add_f32 v[134:135], v[134:135], 1.0 op_sel_hi:[1,0]
	v_log_f32_e32 v136, v132
	v_log_f32_e32 v137, v133
	v_log_f32_e32 v138, v134
	v_log_f32_e32 v139, v135
	v_min_f32_e32 v128, 0, v128
	v_min_f32_e32 v129, 0, v129
	v_min_f32_e32 v130, 0, v130
	v_min_f32_e32 v131, 0, v131
	v_pk_fma_f32 v[98:99], v[136:137], s[36:37], v[128:129] op_sel:[0,1,0] op_sel_hi:[1,1,1]
	v_pk_fma_f32 v[114:115], v[138:139], s[36:37], v[130:131] op_sel:[0,1,0] op_sel_hi:[1,1,1]
	s_waitcnt lgkmcnt(0)
	v_pk_fma_f32 v[128:129], v[10:11], v[216:217], v[74:75] op_sel_hi:[1,0,1]
	v_pk_fma_f32 v[128:129], v[12:13], v[216:217], v[128:129] op_sel:[0,1,0] op_sel_hi:[1,1,1]
	v_pk_fma_f32 v[128:129], v[14:15], v[218:219], v[128:129] op_sel_hi:[1,0,1]
	v_pk_fma_f32 v[128:129], v[16:17], v[218:219], v[128:129] op_sel:[0,1,0] op_sel_hi:[1,1,1]
	v_pk_fma_f32 v[128:129], v[18:19], v[220:221], v[128:129] op_sel_hi:[1,0,1]
	v_pk_fma_f32 v[128:129], v[20:21], v[220:221], v[128:129] op_sel:[0,1,0] op_sel_hi:[1,1,1]
	v_pk_fma_f32 v[128:129], v[22:23], v[222:223], v[128:129] op_sel_hi:[1,0,1]
	v_pk_fma_f32 v[128:129], v[24:25], v[222:223], v[128:129] op_sel:[0,1,0] op_sel_hi:[1,1,1]
	v_pk_fma_f32 v[128:129], v[26:27], v[224:225], v[128:129] op_sel_hi:[1,0,1]
	v_pk_fma_f32 v[128:129], v[28:29], v[224:225], v[128:129] op_sel:[0,1,0] op_sel_hi:[1,1,1]
	v_pk_fma_f32 v[128:129], v[30:31], v[226:227], v[128:129] op_sel_hi:[1,0,1]
	v_pk_fma_f32 v[128:129], v[32:33], v[226:227], v[128:129] op_sel:[0,1,0] op_sel_hi:[1,1,1]
	v_pk_fma_f32 v[128:129], v[34:35], v[228:229], v[128:129] op_sel_hi:[1,0,1]
	v_pk_fma_f32 v[128:129], v[36:37], v[228:229], v[128:129] op_sel:[0,1,0] op_sel_hi:[1,1,1]
	v_pk_fma_f32 v[128:129], v[38:39], v[230:231], v[128:129] op_sel_hi:[1,0,1]
	v_pk_fma_f32 v[128:129], v[40:41], v[230:231], v[128:129] op_sel:[0,1,0] op_sel_hi:[1,1,1]
	ds_read_b128 v[216:219], v78 offset:384
	ds_read_b128 v[220:223], v78 offset:400
	ds_read_b128 v[224:227], v78 offset:416
	ds_read_b128 v[228:231], v78 offset:432
	v_pk_fma_f32 v[130:131], v[42:43], v[232:233], v[76:77] op_sel_hi:[1,0,1]
	v_pk_fma_f32 v[130:131], v[44:45], v[232:233], v[130:131] op_sel:[0,1,0] op_sel_hi:[1,1,1]
	v_pk_fma_f32 v[130:131], v[46:47], v[234:235], v[130:131] op_sel_hi:[1,0,1]
	v_pk_fma_f32 v[130:131], v[48:49], v[234:235], v[130:131] op_sel:[0,1,0] op_sel_hi:[1,1,1]
	v_pk_fma_f32 v[130:131], v[50:51], v[236:237], v[130:131] op_sel_hi:[1,0,1]
	v_pk_fma_f32 v[130:131], v[52:53], v[236:237], v[130:131] op_sel:[0,1,0] op_sel_hi:[1,1,1]
	v_pk_fma_f32 v[130:131], v[54:55], v[238:239], v[130:131] op_sel_hi:[1,0,1]
	v_pk_fma_f32 v[130:131], v[56:57], v[238:239], v[130:131] op_sel:[0,1,0] op_sel_hi:[1,1,1]
	v_pk_fma_f32 v[130:131], v[58:59], v[240:241], v[130:131] op_sel_hi:[1,0,1]
	v_pk_fma_f32 v[130:131], v[60:61], v[240:241], v[130:131] op_sel:[0,1,0] op_sel_hi:[1,1,1]
	v_pk_fma_f32 v[130:131], v[62:63], v[242:243], v[130:131] op_sel_hi:[1,0,1]
	v_pk_fma_f32 v[130:131], v[64:65], v[242:243], v[130:131] op_sel:[0,1,0] op_sel_hi:[1,1,1]
	v_pk_fma_f32 v[130:131], v[66:67], v[244:245], v[130:131] op_sel_hi:[1,0,1]
	v_pk_fma_f32 v[130:131], v[68:69], v[244:245], v[130:131] op_sel:[0,1,0] op_sel_hi:[1,1,1]
	v_pk_fma_f32 v[130:131], v[70:71], v[246:247], v[130:131] op_sel_hi:[1,0,1]
	v_pk_fma_f32 v[130:131], v[72:73], v[246:247], v[130:131] op_sel:[0,1,0] op_sel_hi:[1,1,1]
	ds_read_b128 v[232:235], v78 offset:448
	ds_read_b128 v[236:239], v78 offset:464
	ds_read_b128 v[240:243], v78 offset:480
	ds_read_b128 v[244:247], v78 offset:496
	v_pk_mul_f32 v[132:133], v[128:129], s[36:37] op_sel_hi:[1,0]
	v_pk_mul_f32 v[134:135], v[130:131], s[36:37] op_sel_hi:[1,0]
	v_exp_f32_e64 v132, -|v132|
	v_exp_f32_e64 v133, -|v133|
	v_exp_f32_e64 v134, -|v134|
	v_exp_f32_e64 v135, -|v135|
	v_pk_add_f32 v[132:133], v[132:133], 1.0 op_sel_hi:[1,0]
	v_pk_add_f32 v[134:135], v[134:135], 1.0 op_sel_hi:[1,0]
	v_log_f32_e32 v136, v132
	v_log_f32_e32 v137, v133
	v_log_f32_e32 v138, v134
	v_log_f32_e32 v139, v135
	v_min_f32_e32 v128, 0, v128
	v_min_f32_e32 v129, 0, v129
	v_min_f32_e32 v130, 0, v130
	v_min_f32_e32 v131, 0, v131
	v_pk_fma_f32 v[100:101], v[136:137], s[36:37], v[128:129] op_sel:[0,1,0] op_sel_hi:[1,1,1]
	v_pk_fma_f32 v[116:117], v[138:139], s[36:37], v[130:131] op_sel:[0,1,0] op_sel_hi:[1,1,1]
	s_waitcnt lgkmcnt(0)
	v_pk_fma_f32 v[128:129], v[10:11], v[216:217], v[74:75] op_sel_hi:[1,0,1]
	v_pk_fma_f32 v[128:129], v[12:13], v[216:217], v[128:129] op_sel:[0,1,0] op_sel_hi:[1,1,1]
	v_pk_fma_f32 v[128:129], v[14:15], v[218:219], v[128:129] op_sel_hi:[1,0,1]
	v_pk_fma_f32 v[128:129], v[16:17], v[218:219], v[128:129] op_sel:[0,1,0] op_sel_hi:[1,1,1]
	v_pk_fma_f32 v[128:129], v[18:19], v[220:221], v[128:129] op_sel_hi:[1,0,1]
	v_pk_fma_f32 v[128:129], v[20:21], v[220:221], v[128:129] op_sel:[0,1,0] op_sel_hi:[1,1,1]
	v_pk_fma_f32 v[128:129], v[22:23], v[222:223], v[128:129] op_sel_hi:[1,0,1]
	v_pk_fma_f32 v[128:129], v[24:25], v[222:223], v[128:129] op_sel:[0,1,0] op_sel_hi:[1,1,1]
	v_pk_fma_f32 v[128:129], v[26:27], v[224:225], v[128:129] op_sel_hi:[1,0,1]
	v_pk_fma_f32 v[128:129], v[28:29], v[224:225], v[128:129] op_sel:[0,1,0] op_sel_hi:[1,1,1]
	v_pk_fma_f32 v[128:129], v[30:31], v[226:227], v[128:129] op_sel_hi:[1,0,1]
	v_pk_fma_f32 v[128:129], v[32:33], v[226:227], v[128:129] op_sel:[0,1,0] op_sel_hi:[1,1,1]
	v_pk_fma_f32 v[128:129], v[34:35], v[228:229], v[128:129] op_sel_hi:[1,0,1]
	v_pk_fma_f32 v[128:129], v[36:37], v[228:229], v[128:129] op_sel:[0,1,0] op_sel_hi:[1,1,1]
	v_pk_fma_f32 v[128:129], v[38:39], v[230:231], v[128:129] op_sel_hi:[1,0,1]
	v_pk_fma_f32 v[128:129], v[40:41], v[230:231], v[128:129] op_sel:[0,1,0] op_sel_hi:[1,1,1]
	ds_read_b128 v[216:219], v78 offset:512
	ds_read_b128 v[220:223], v78 offset:528
	ds_read_b128 v[224:227], v78 offset:544
	ds_read_b128 v[228:231], v78 offset:560
	v_pk_fma_f32 v[130:131], v[42:43], v[232:233], v[76:77] op_sel_hi:[1,0,1]
	v_pk_fma_f32 v[130:131], v[44:45], v[232:233], v[130:131] op_sel:[0,1,0] op_sel_hi:[1,1,1]
	v_pk_fma_f32 v[130:131], v[46:47], v[234:235], v[130:131] op_sel_hi:[1,0,1]
	v_pk_fma_f32 v[130:131], v[48:49], v[234:235], v[130:131] op_sel:[0,1,0] op_sel_hi:[1,1,1]
	v_pk_fma_f32 v[130:131], v[50:51], v[236:237], v[130:131] op_sel_hi:[1,0,1]
	v_pk_fma_f32 v[130:131], v[52:53], v[236:237], v[130:131] op_sel:[0,1,0] op_sel_hi:[1,1,1]
	v_pk_fma_f32 v[130:131], v[54:55], v[238:239], v[130:131] op_sel_hi:[1,0,1]
	v_pk_fma_f32 v[130:131], v[56:57], v[238:239], v[130:131] op_sel:[0,1,0] op_sel_hi:[1,1,1]
	v_pk_fma_f32 v[130:131], v[58:59], v[240:241], v[130:131] op_sel_hi:[1,0,1]
	v_pk_fma_f32 v[130:131], v[60:61], v[240:241], v[130:131] op_sel:[0,1,0] op_sel_hi:[1,1,1]
	v_pk_fma_f32 v[130:131], v[62:63], v[242:243], v[130:131] op_sel_hi:[1,0,1]
	v_pk_fma_f32 v[130:131], v[64:65], v[242:243], v[130:131] op_sel:[0,1,0] op_sel_hi:[1,1,1]
	v_pk_fma_f32 v[130:131], v[66:67], v[244:245], v[130:131] op_sel_hi:[1,0,1]
	v_pk_fma_f32 v[130:131], v[68:69], v[244:245], v[130:131] op_sel:[0,1,0] op_sel_hi:[1,1,1]
	v_pk_fma_f32 v[130:131], v[70:71], v[246:247], v[130:131] op_sel_hi:[1,0,1]
	v_pk_fma_f32 v[130:131], v[72:73], v[246:247], v[130:131] op_sel:[0,1,0] op_sel_hi:[1,1,1]
	ds_read_b128 v[232:235], v78 offset:576
	ds_read_b128 v[236:239], v78 offset:592
	ds_read_b128 v[240:243], v78 offset:608
	ds_read_b128 v[244:247], v78 offset:624
	v_pk_mul_f32 v[132:133], v[128:129], s[36:37] op_sel_hi:[1,0]
	v_pk_mul_f32 v[134:135], v[130:131], s[36:37] op_sel_hi:[1,0]
	v_exp_f32_e64 v132, -|v132|
	v_exp_f32_e64 v133, -|v133|
	v_exp_f32_e64 v134, -|v134|
	v_exp_f32_e64 v135, -|v135|
	v_pk_add_f32 v[132:133], v[132:133], 1.0 op_sel_hi:[1,0]
	v_pk_add_f32 v[134:135], v[134:135], 1.0 op_sel_hi:[1,0]
	v_log_f32_e32 v136, v132
	v_log_f32_e32 v137, v133
	v_log_f32_e32 v138, v134
	v_log_f32_e32 v139, v135
	v_min_f32_e32 v128, 0, v128
	v_min_f32_e32 v129, 0, v129
	v_min_f32_e32 v130, 0, v130
	v_min_f32_e32 v131, 0, v131
	v_pk_fma_f32 v[102:103], v[136:137], s[36:37], v[128:129] op_sel:[0,1,0] op_sel_hi:[1,1,1]
	v_pk_fma_f32 v[118:119], v[138:139], s[36:37], v[130:131] op_sel:[0,1,0] op_sel_hi:[1,1,1]
	s_waitcnt lgkmcnt(0)
	v_pk_fma_f32 v[128:129], v[10:11], v[216:217], v[74:75] op_sel_hi:[1,0,1]
	v_pk_fma_f32 v[128:129], v[12:13], v[216:217], v[128:129] op_sel:[0,1,0] op_sel_hi:[1,1,1]
	v_pk_fma_f32 v[128:129], v[14:15], v[218:219], v[128:129] op_sel_hi:[1,0,1]
	v_pk_fma_f32 v[128:129], v[16:17], v[218:219], v[128:129] op_sel:[0,1,0] op_sel_hi:[1,1,1]
	v_pk_fma_f32 v[128:129], v[18:19], v[220:221], v[128:129] op_sel_hi:[1,0,1]
	v_pk_fma_f32 v[128:129], v[20:21], v[220:221], v[128:129] op_sel:[0,1,0] op_sel_hi:[1,1,1]
	v_pk_fma_f32 v[128:129], v[22:23], v[222:223], v[128:129] op_sel_hi:[1,0,1]
	v_pk_fma_f32 v[128:129], v[24:25], v[222:223], v[128:129] op_sel:[0,1,0] op_sel_hi:[1,1,1]
	v_pk_fma_f32 v[128:129], v[26:27], v[224:225], v[128:129] op_sel_hi:[1,0,1]
	v_pk_fma_f32 v[128:129], v[28:29], v[224:225], v[128:129] op_sel:[0,1,0] op_sel_hi:[1,1,1]
	v_pk_fma_f32 v[128:129], v[30:31], v[226:227], v[128:129] op_sel_hi:[1,0,1]
	v_pk_fma_f32 v[128:129], v[32:33], v[226:227], v[128:129] op_sel:[0,1,0] op_sel_hi:[1,1,1]
	v_pk_fma_f32 v[128:129], v[34:35], v[228:229], v[128:129] op_sel_hi:[1,0,1]
	v_pk_fma_f32 v[128:129], v[36:37], v[228:229], v[128:129] op_sel:[0,1,0] op_sel_hi:[1,1,1]
	v_pk_fma_f32 v[128:129], v[38:39], v[230:231], v[128:129] op_sel_hi:[1,0,1]
	v_pk_fma_f32 v[128:129], v[40:41], v[230:231], v[128:129] op_sel:[0,1,0] op_sel_hi:[1,1,1]
	ds_read_b128 v[216:219], v78 offset:640
	ds_read_b128 v[220:223], v78 offset:656
	ds_read_b128 v[224:227], v78 offset:672
	ds_read_b128 v[228:231], v78 offset:688
	v_pk_fma_f32 v[130:131], v[42:43], v[232:233], v[76:77] op_sel_hi:[1,0,1]
	v_pk_fma_f32 v[130:131], v[44:45], v[232:233], v[130:131] op_sel:[0,1,0] op_sel_hi:[1,1,1]
	v_pk_fma_f32 v[130:131], v[46:47], v[234:235], v[130:131] op_sel_hi:[1,0,1]
	v_pk_fma_f32 v[130:131], v[48:49], v[234:235], v[130:131] op_sel:[0,1,0] op_sel_hi:[1,1,1]
	v_pk_fma_f32 v[130:131], v[50:51], v[236:237], v[130:131] op_sel_hi:[1,0,1]
	v_pk_fma_f32 v[130:131], v[52:53], v[236:237], v[130:131] op_sel:[0,1,0] op_sel_hi:[1,1,1]
	v_pk_fma_f32 v[130:131], v[54:55], v[238:239], v[130:131] op_sel_hi:[1,0,1]
	v_pk_fma_f32 v[130:131], v[56:57], v[238:239], v[130:131] op_sel:[0,1,0] op_sel_hi:[1,1,1]
	v_pk_fma_f32 v[130:131], v[58:59], v[240:241], v[130:131] op_sel_hi:[1,0,1]
	v_pk_fma_f32 v[130:131], v[60:61], v[240:241], v[130:131] op_sel:[0,1,0] op_sel_hi:[1,1,1]
	v_pk_fma_f32 v[130:131], v[62:63], v[242:243], v[130:131] op_sel_hi:[1,0,1]
	v_pk_fma_f32 v[130:131], v[64:65], v[242:243], v[130:131] op_sel:[0,1,0] op_sel_hi:[1,1,1]
	v_pk_fma_f32 v[130:131], v[66:67], v[244:245], v[130:131] op_sel_hi:[1,0,1]
	v_pk_fma_f32 v[130:131], v[68:69], v[244:245], v[130:131] op_sel:[0,1,0] op_sel_hi:[1,1,1]
	v_pk_fma_f32 v[130:131], v[70:71], v[246:247], v[130:131] op_sel_hi:[1,0,1]
	v_pk_fma_f32 v[130:131], v[72:73], v[246:247], v[130:131] op_sel:[0,1,0] op_sel_hi:[1,1,1]
	ds_read_b128 v[232:235], v78 offset:704
	ds_read_b128 v[236:239], v78 offset:720
	ds_read_b128 v[240:243], v78 offset:736
	ds_read_b128 v[244:247], v78 offset:752
	v_pk_mul_f32 v[132:133], v[128:129], s[36:37] op_sel_hi:[1,0]
	v_pk_mul_f32 v[134:135], v[130:131], s[36:37] op_sel_hi:[1,0]
	v_exp_f32_e64 v132, -|v132|
	v_exp_f32_e64 v133, -|v133|
	v_exp_f32_e64 v134, -|v134|
	v_exp_f32_e64 v135, -|v135|
	v_pk_add_f32 v[132:133], v[132:133], 1.0 op_sel_hi:[1,0]
	v_pk_add_f32 v[134:135], v[134:135], 1.0 op_sel_hi:[1,0]
	v_log_f32_e32 v136, v132
	v_log_f32_e32 v137, v133
	v_log_f32_e32 v138, v134
	v_log_f32_e32 v139, v135
	v_min_f32_e32 v128, 0, v128
	v_min_f32_e32 v129, 0, v129
	v_min_f32_e32 v130, 0, v130
	v_min_f32_e32 v131, 0, v131
	v_pk_fma_f32 v[104:105], v[136:137], s[36:37], v[128:129] op_sel:[0,1,0] op_sel_hi:[1,1,1]
	v_pk_fma_f32 v[120:121], v[138:139], s[36:37], v[130:131] op_sel:[0,1,0] op_sel_hi:[1,1,1]
	s_waitcnt lgkmcnt(0)
	v_pk_fma_f32 v[128:129], v[10:11], v[216:217], v[74:75] op_sel_hi:[1,0,1]
	v_pk_fma_f32 v[128:129], v[12:13], v[216:217], v[128:129] op_sel:[0,1,0] op_sel_hi:[1,1,1]
	v_pk_fma_f32 v[128:129], v[14:15], v[218:219], v[128:129] op_sel_hi:[1,0,1]
	v_pk_fma_f32 v[128:129], v[16:17], v[218:219], v[128:129] op_sel:[0,1,0] op_sel_hi:[1,1,1]
	v_pk_fma_f32 v[128:129], v[18:19], v[220:221], v[128:129] op_sel_hi:[1,0,1]
	v_pk_fma_f32 v[128:129], v[20:21], v[220:221], v[128:129] op_sel:[0,1,0] op_sel_hi:[1,1,1]
	v_pk_fma_f32 v[128:129], v[22:23], v[222:223], v[128:129] op_sel_hi:[1,0,1]
	v_pk_fma_f32 v[128:129], v[24:25], v[222:223], v[128:129] op_sel:[0,1,0] op_sel_hi:[1,1,1]
	v_pk_fma_f32 v[128:129], v[26:27], v[224:225], v[128:129] op_sel_hi:[1,0,1]
	v_pk_fma_f32 v[128:129], v[28:29], v[224:225], v[128:129] op_sel:[0,1,0] op_sel_hi:[1,1,1]
	v_pk_fma_f32 v[128:129], v[30:31], v[226:227], v[128:129] op_sel_hi:[1,0,1]
	v_pk_fma_f32 v[128:129], v[32:33], v[226:227], v[128:129] op_sel:[0,1,0] op_sel_hi:[1,1,1]
	v_pk_fma_f32 v[128:129], v[34:35], v[228:229], v[128:129] op_sel_hi:[1,0,1]
	v_pk_fma_f32 v[128:129], v[36:37], v[228:229], v[128:129] op_sel:[0,1,0] op_sel_hi:[1,1,1]
	v_pk_fma_f32 v[128:129], v[38:39], v[230:231], v[128:129] op_sel_hi:[1,0,1]
	v_pk_fma_f32 v[128:129], v[40:41], v[230:231], v[128:129] op_sel:[0,1,0] op_sel_hi:[1,1,1]
	ds_read_b128 v[216:219], v78 offset:768
	ds_read_b128 v[220:223], v78 offset:784
	ds_read_b128 v[224:227], v78 offset:800
	ds_read_b128 v[228:231], v78 offset:816
	v_pk_fma_f32 v[130:131], v[42:43], v[232:233], v[76:77] op_sel_hi:[1,0,1]
	v_pk_fma_f32 v[130:131], v[44:45], v[232:233], v[130:131] op_sel:[0,1,0] op_sel_hi:[1,1,1]
	v_pk_fma_f32 v[130:131], v[46:47], v[234:235], v[130:131] op_sel_hi:[1,0,1]
	v_pk_fma_f32 v[130:131], v[48:49], v[234:235], v[130:131] op_sel:[0,1,0] op_sel_hi:[1,1,1]
	v_pk_fma_f32 v[130:131], v[50:51], v[236:237], v[130:131] op_sel_hi:[1,0,1]
	v_pk_fma_f32 v[130:131], v[52:53], v[236:237], v[130:131] op_sel:[0,1,0] op_sel_hi:[1,1,1]
	v_pk_fma_f32 v[130:131], v[54:55], v[238:239], v[130:131] op_sel_hi:[1,0,1]
	v_pk_fma_f32 v[130:131], v[56:57], v[238:239], v[130:131] op_sel:[0,1,0] op_sel_hi:[1,1,1]
	v_pk_fma_f32 v[130:131], v[58:59], v[240:241], v[130:131] op_sel_hi:[1,0,1]
	v_pk_fma_f32 v[130:131], v[60:61], v[240:241], v[130:131] op_sel:[0,1,0] op_sel_hi:[1,1,1]
	v_pk_fma_f32 v[130:131], v[62:63], v[242:243], v[130:131] op_sel_hi:[1,0,1]
	v_pk_fma_f32 v[130:131], v[64:65], v[242:243], v[130:131] op_sel:[0,1,0] op_sel_hi:[1,1,1]
	v_pk_fma_f32 v[130:131], v[66:67], v[244:245], v[130:131] op_sel_hi:[1,0,1]
	v_pk_fma_f32 v[130:131], v[68:69], v[244:245], v[130:131] op_sel:[0,1,0] op_sel_hi:[1,1,1]
	v_pk_fma_f32 v[130:131], v[70:71], v[246:247], v[130:131] op_sel_hi:[1,0,1]
	v_pk_fma_f32 v[130:131], v[72:73], v[246:247], v[130:131] op_sel:[0,1,0] op_sel_hi:[1,1,1]
	ds_read_b128 v[232:235], v78 offset:832
	ds_read_b128 v[236:239], v78 offset:848
	ds_read_b128 v[240:243], v78 offset:864
	ds_read_b128 v[244:247], v78 offset:880
	v_pk_mul_f32 v[132:133], v[128:129], s[36:37] op_sel_hi:[1,0]
	v_pk_mul_f32 v[134:135], v[130:131], s[36:37] op_sel_hi:[1,0]
	v_exp_f32_e64 v132, -|v132|
	v_exp_f32_e64 v133, -|v133|
	v_exp_f32_e64 v134, -|v134|
	v_exp_f32_e64 v135, -|v135|
	v_pk_add_f32 v[132:133], v[132:133], 1.0 op_sel_hi:[1,0]
	v_pk_add_f32 v[134:135], v[134:135], 1.0 op_sel_hi:[1,0]
	v_log_f32_e32 v136, v132
	v_log_f32_e32 v137, v133
	v_log_f32_e32 v138, v134
	v_log_f32_e32 v139, v135
	v_min_f32_e32 v128, 0, v128
	v_min_f32_e32 v129, 0, v129
	v_min_f32_e32 v130, 0, v130
	v_min_f32_e32 v131, 0, v131
	v_pk_fma_f32 v[106:107], v[136:137], s[36:37], v[128:129] op_sel:[0,1,0] op_sel_hi:[1,1,1]
	v_pk_fma_f32 v[122:123], v[138:139], s[36:37], v[130:131] op_sel:[0,1,0] op_sel_hi:[1,1,1]
	s_waitcnt lgkmcnt(0)
	v_pk_fma_f32 v[128:129], v[10:11], v[216:217], v[74:75] op_sel_hi:[1,0,1]
	v_pk_fma_f32 v[128:129], v[12:13], v[216:217], v[128:129] op_sel:[0,1,0] op_sel_hi:[1,1,1]
	v_pk_fma_f32 v[128:129], v[14:15], v[218:219], v[128:129] op_sel_hi:[1,0,1]
	v_pk_fma_f32 v[128:129], v[16:17], v[218:219], v[128:129] op_sel:[0,1,0] op_sel_hi:[1,1,1]
	v_pk_fma_f32 v[128:129], v[18:19], v[220:221], v[128:129] op_sel_hi:[1,0,1]
	v_pk_fma_f32 v[128:129], v[20:21], v[220:221], v[128:129] op_sel:[0,1,0] op_sel_hi:[1,1,1]
	v_pk_fma_f32 v[128:129], v[22:23], v[222:223], v[128:129] op_sel_hi:[1,0,1]
	v_pk_fma_f32 v[128:129], v[24:25], v[222:223], v[128:129] op_sel:[0,1,0] op_sel_hi:[1,1,1]
	v_pk_fma_f32 v[128:129], v[26:27], v[224:225], v[128:129] op_sel_hi:[1,0,1]
	v_pk_fma_f32 v[128:129], v[28:29], v[224:225], v[128:129] op_sel:[0,1,0] op_sel_hi:[1,1,1]
	v_pk_fma_f32 v[128:129], v[30:31], v[226:227], v[128:129] op_sel_hi:[1,0,1]
	v_pk_fma_f32 v[128:129], v[32:33], v[226:227], v[128:129] op_sel:[0,1,0] op_sel_hi:[1,1,1]
	v_pk_fma_f32 v[128:129], v[34:35], v[228:229], v[128:129] op_sel_hi:[1,0,1]
	v_pk_fma_f32 v[128:129], v[36:37], v[228:229], v[128:129] op_sel:[0,1,0] op_sel_hi:[1,1,1]
	v_pk_fma_f32 v[128:129], v[38:39], v[230:231], v[128:129] op_sel_hi:[1,0,1]
	v_pk_fma_f32 v[128:129], v[40:41], v[230:231], v[128:129] op_sel:[0,1,0] op_sel_hi:[1,1,1]
	ds_read_b128 v[216:219], v78 offset:896
	ds_read_b128 v[220:223], v78 offset:912
	ds_read_b128 v[224:227], v78 offset:928
	ds_read_b128 v[228:231], v78 offset:944
	v_pk_fma_f32 v[130:131], v[42:43], v[232:233], v[76:77] op_sel_hi:[1,0,1]
	v_pk_fma_f32 v[130:131], v[44:45], v[232:233], v[130:131] op_sel:[0,1,0] op_sel_hi:[1,1,1]
	v_pk_fma_f32 v[130:131], v[46:47], v[234:235], v[130:131] op_sel_hi:[1,0,1]
	v_pk_fma_f32 v[130:131], v[48:49], v[234:235], v[130:131] op_sel:[0,1,0] op_sel_hi:[1,1,1]
	v_pk_fma_f32 v[130:131], v[50:51], v[236:237], v[130:131] op_sel_hi:[1,0,1]
	v_pk_fma_f32 v[130:131], v[52:53], v[236:237], v[130:131] op_sel:[0,1,0] op_sel_hi:[1,1,1]
	v_pk_fma_f32 v[130:131], v[54:55], v[238:239], v[130:131] op_sel_hi:[1,0,1]
	v_pk_fma_f32 v[130:131], v[56:57], v[238:239], v[130:131] op_sel:[0,1,0] op_sel_hi:[1,1,1]
	v_pk_fma_f32 v[130:131], v[58:59], v[240:241], v[130:131] op_sel_hi:[1,0,1]
	v_pk_fma_f32 v[130:131], v[60:61], v[240:241], v[130:131] op_sel:[0,1,0] op_sel_hi:[1,1,1]
	v_pk_fma_f32 v[130:131], v[62:63], v[242:243], v[130:131] op_sel_hi:[1,0,1]
	v_pk_fma_f32 v[130:131], v[64:65], v[242:243], v[130:131] op_sel:[0,1,0] op_sel_hi:[1,1,1]
	v_pk_fma_f32 v[130:131], v[66:67], v[244:245], v[130:131] op_sel_hi:[1,0,1]
	v_pk_fma_f32 v[130:131], v[68:69], v[244:245], v[130:131] op_sel:[0,1,0] op_sel_hi:[1,1,1]
	v_pk_fma_f32 v[130:131], v[70:71], v[246:247], v[130:131] op_sel_hi:[1,0,1]
	v_pk_fma_f32 v[130:131], v[72:73], v[246:247], v[130:131] op_sel:[0,1,0] op_sel_hi:[1,1,1]
	ds_read_b128 v[232:235], v78 offset:960
	ds_read_b128 v[236:239], v78 offset:976
	ds_read_b128 v[240:243], v78 offset:992
	ds_read_b128 v[244:247], v78 offset:1008
	v_pk_mul_f32 v[132:133], v[128:129], s[36:37] op_sel_hi:[1,0]
	v_pk_mul_f32 v[134:135], v[130:131], s[36:37] op_sel_hi:[1,0]
	v_exp_f32_e64 v132, -|v132|
	v_exp_f32_e64 v133, -|v133|
	v_exp_f32_e64 v134, -|v134|
	v_exp_f32_e64 v135, -|v135|
	v_pk_add_f32 v[132:133], v[132:133], 1.0 op_sel_hi:[1,0]
	v_pk_add_f32 v[134:135], v[134:135], 1.0 op_sel_hi:[1,0]
	v_log_f32_e32 v136, v132
	v_log_f32_e32 v137, v133
	v_log_f32_e32 v138, v134
	v_log_f32_e32 v139, v135
	v_min_f32_e32 v128, 0, v128
	v_min_f32_e32 v129, 0, v129
	v_min_f32_e32 v130, 0, v130
	v_min_f32_e32 v131, 0, v131
	v_pk_fma_f32 v[108:109], v[136:137], s[36:37], v[128:129] op_sel:[0,1,0] op_sel_hi:[1,1,1]
	v_pk_fma_f32 v[124:125], v[138:139], s[36:37], v[130:131] op_sel:[0,1,0] op_sel_hi:[1,1,1]
	s_waitcnt lgkmcnt(0)
	v_pk_fma_f32 v[128:129], v[10:11], v[216:217], v[74:75] op_sel_hi:[1,0,1]
	v_pk_fma_f32 v[128:129], v[12:13], v[216:217], v[128:129] op_sel:[0,1,0] op_sel_hi:[1,1,1]
	v_pk_fma_f32 v[128:129], v[14:15], v[218:219], v[128:129] op_sel_hi:[1,0,1]
	v_pk_fma_f32 v[128:129], v[16:17], v[218:219], v[128:129] op_sel:[0,1,0] op_sel_hi:[1,1,1]
	v_pk_fma_f32 v[128:129], v[18:19], v[220:221], v[128:129] op_sel_hi:[1,0,1]
	v_pk_fma_f32 v[128:129], v[20:21], v[220:221], v[128:129] op_sel:[0,1,0] op_sel_hi:[1,1,1]
	v_pk_fma_f32 v[128:129], v[22:23], v[222:223], v[128:129] op_sel_hi:[1,0,1]
	v_pk_fma_f32 v[128:129], v[24:25], v[222:223], v[128:129] op_sel:[0,1,0] op_sel_hi:[1,1,1]
	v_pk_fma_f32 v[128:129], v[26:27], v[224:225], v[128:129] op_sel_hi:[1,0,1]
	v_pk_fma_f32 v[128:129], v[28:29], v[224:225], v[128:129] op_sel:[0,1,0] op_sel_hi:[1,1,1]
	v_pk_fma_f32 v[128:129], v[30:31], v[226:227], v[128:129] op_sel_hi:[1,0,1]
	v_pk_fma_f32 v[128:129], v[32:33], v[226:227], v[128:129] op_sel:[0,1,0] op_sel_hi:[1,1,1]
	v_pk_fma_f32 v[128:129], v[34:35], v[228:229], v[128:129] op_sel_hi:[1,0,1]
	v_pk_fma_f32 v[128:129], v[36:37], v[228:229], v[128:129] op_sel:[0,1,0] op_sel_hi:[1,1,1]
	v_pk_fma_f32 v[128:129], v[38:39], v[230:231], v[128:129] op_sel_hi:[1,0,1]
	v_pk_fma_f32 v[128:129], v[40:41], v[230:231], v[128:129] op_sel:[0,1,0] op_sel_hi:[1,1,1]
	v_pk_fma_f32 v[130:131], v[42:43], v[232:233], v[76:77] op_sel_hi:[1,0,1]
	v_pk_fma_f32 v[130:131], v[44:45], v[232:233], v[130:131] op_sel:[0,1,0] op_sel_hi:[1,1,1]
	v_pk_fma_f32 v[130:131], v[46:47], v[234:235], v[130:131] op_sel_hi:[1,0,1]
	v_pk_fma_f32 v[130:131], v[48:49], v[234:235], v[130:131] op_sel:[0,1,0] op_sel_hi:[1,1,1]
	v_pk_fma_f32 v[130:131], v[50:51], v[236:237], v[130:131] op_sel_hi:[1,0,1]
	v_pk_fma_f32 v[130:131], v[52:53], v[236:237], v[130:131] op_sel:[0,1,0] op_sel_hi:[1,1,1]
	v_pk_fma_f32 v[130:131], v[54:55], v[238:239], v[130:131] op_sel_hi:[1,0,1]
	v_pk_fma_f32 v[130:131], v[56:57], v[238:239], v[130:131] op_sel:[0,1,0] op_sel_hi:[1,1,1]
	v_pk_fma_f32 v[130:131], v[58:59], v[240:241], v[130:131] op_sel_hi:[1,0,1]
	v_pk_fma_f32 v[130:131], v[60:61], v[240:241], v[130:131] op_sel:[0,1,0] op_sel_hi:[1,1,1]
	v_pk_fma_f32 v[130:131], v[62:63], v[242:243], v[130:131] op_sel_hi:[1,0,1]
	v_pk_fma_f32 v[130:131], v[64:65], v[242:243], v[130:131] op_sel:[0,1,0] op_sel_hi:[1,1,1]
	v_pk_fma_f32 v[130:131], v[66:67], v[244:245], v[130:131] op_sel_hi:[1,0,1]
	v_pk_fma_f32 v[130:131], v[68:69], v[244:245], v[130:131] op_sel:[0,1,0] op_sel_hi:[1,1,1]
	v_pk_fma_f32 v[130:131], v[70:71], v[246:247], v[130:131] op_sel_hi:[1,0,1]
	v_pk_fma_f32 v[130:131], v[72:73], v[246:247], v[130:131] op_sel:[0,1,0] op_sel_hi:[1,1,1]
	v_pk_mul_f32 v[132:133], v[128:129], s[36:37] op_sel_hi:[1,0]
	v_pk_mul_f32 v[134:135], v[130:131], s[36:37] op_sel_hi:[1,0]
	v_exp_f32_e64 v132, -|v132|
	v_exp_f32_e64 v133, -|v133|
	v_exp_f32_e64 v134, -|v134|
	v_exp_f32_e64 v135, -|v135|
	v_pk_add_f32 v[132:133], v[132:133], 1.0 op_sel_hi:[1,0]
	v_pk_add_f32 v[134:135], v[134:135], 1.0 op_sel_hi:[1,0]
	v_log_f32_e32 v136, v132
	v_log_f32_e32 v137, v133
	v_log_f32_e32 v138, v134
	v_log_f32_e32 v139, v135
	v_min_f32_e32 v128, 0, v128
	v_min_f32_e32 v129, 0, v129
	v_min_f32_e32 v130, 0, v130
	v_min_f32_e32 v131, 0, v131
	v_pk_fma_f32 v[110:111], v[136:137], s[36:37], v[128:129] op_sel:[0,1,0] op_sel_hi:[1,1,1]
	v_pk_fma_f32 v[126:127], v[138:139], s[36:37], v[130:131] op_sel:[0,1,0] op_sel_hi:[1,1,1]
	s_waitcnt vmcnt(16)
	v_mov_b32_e32 v80, v200
	v_mov_b32_e32 v81, v201
	v_mov_b32_e32 v82, v202
	v_mov_b32_e32 v83, v203
	v_mov_b32_e32 v84, v204
	v_mov_b32_e32 v85, v205
	v_mov_b32_e32 v86, v206
	v_mov_b32_e32 v87, v207
	v_mov_b32_e32 v88, v208
	v_mov_b32_e32 v89, v209
	v_mov_b32_e32 v90, v210
	v_mov_b32_e32 v91, v211
	v_mov_b32_e32 v92, v212
	v_mov_b32_e32 v93, v213
	v_mov_b32_e32 v94, v214
	v_mov_b32_e32 v95, v215
	v_readlane_b32 s69, v251, 49
	s_nop 3
	s_add_i32 s56, s56, 64
	s_movk_i32 s51, 0x480
	s_cmpk_lt_i32 s56, 0x120
	s_cbranch_scc0 .Lp7_jdone
	s_mul_hi_u32 s57, s56, 0x71c71c8
	s_mul_i32 s51, s57, 108
	s_add_i32 s51, s51, s56
	s_and_b32 s57, s58, 3
	s_mul_i32 s57, s57, 36
	s_add_i32 s51, s51, s57

.Lp7_noq_store:
	s_cmpk_lt_i32 s51, 0x480
	s_cbranch_scc0 .Lp7_exit
	s_cmp_lt_u32 s81, 4
	s_cbranch_scc1 .Lp7_wn_ctx
	s_cmp_lt_u32 s39, 4
	s_cbranch_scc1 .Lp7_w32
	s_waitcnt vmcnt(48)
	s_branch .Lp7_wdone
.Lp7_w32:
	s_waitcnt vmcnt(32)
	s_branch .Lp7_wdone
.Lp7_wn_ctx:
	s_cmp_lt_u32 s39, 4
	s_cbranch_scc1 .Lp7_w24
	s_waitcnt vmcnt(40)
	s_branch .Lp7_wdone
.Lp7_w24:
	s_waitcnt vmcnt(24)
.Lp7_wdone:
	s_mov_b32 s34, s51
	s_xor_b32 s50, s50, 1
	s_mov_b32 s38, s80
	s_mov_b32 s39, s81
	s_mov_b32 s40, s82
	s_mov_b32 s41, s83
	s_mov_b64 s[42:43], s[84:85]
	s_mov_b64 s[44:45], s[86:87]
	s_mov_b64 s[46:47], s[98:99]
	s_mov_b64 s[48:49], s[100:101]
	s_branch .Lp7_item
